# v18 plus one s_nop restoring the 12 wait states between the last QK MFMA and the first softmax exp in the A1 A-stream
# speedup vs baseline: 1.0117x; 1.0065x over previous
; template <int NHQ, int NHKV>
; DI void attn_phase_l1(const u16* __restrict__ Q, const u16* __restrict__ K, const u16* __restrict__ Vt, u16* __restrict__ O, const float* __restrict__ qg, char* smem, const int wv) {
;     ...
;         constexpr int NQK = 2 * NS, NM = NQK + 16, RING = 8;
;         const char* sk = kb0 + ((j + 1) & 1) * KBYTES + r32 * KSTR + hh * 16;
;         const char* sv = vb0 + (j & 1) * VBYTES + r32 * VSTR + hh * 16;
;         bf16x8 ring[RING];
;         unsigned w_[16]; f32x2 ps2 = {0.f, 0.f};
;     ...
; #pragma unroll
;         for (int i = 0; i < 16; ++i) { s0[i] = 0.f; s1[i] = 0.f; }
; #pragma unroll
;         for (int i = 0; i < RING; ++i) B_FRAG(ring[i], i);
; #pragma unroll
;         for (int i = 0; i < NM; ++i) {
;           if (i < NQK) {
;             if (i & 1) s1 = __builtin_amdgcn_mfma_f32_32x32x16_bf16(ring[i % RING], qf[i >> 1], s1, 0, 0, 0);
;             else       s0 = __builtin_amdgcn_mfma_f32_32x32x16_bf16(ring[i % RING], qf[i >> 1], s0, 0, 0, 0);
;           } else {
;             o[(i - NQK) & 3] = __builtin_amdgcn_mfma_f32_32x32x16_bf16(ring[i % RING], pb[(i - NQK) >> 2], o[(i - NQK) & 3], 0, 0, 0);
;           }
;           if (i + RING < NM) B_FRAG(ring[i % RING], i + RING);
;           if (i >= NQK + 2) {
;             const int g = i - NQK - 2;
;             f32x2 v;
;             if (g < 8) { v[0] = __builtin_amdgcn_exp2f(s0[2 * g]); v[1] = __builtin_amdgcn_exp2f(s0[2 * g + 1]); }
;             else       { v[0] = __builtin_amdgcn_exp2f(s1[2 * (g - 8)]); v[1] = __builtin_amdgcn_exp2f(s1[2 * (g - 8) + 1]); }
;             ps2 += v; w_[g] = cvtpk(v[0], v[1]);
;           }
;           __builtin_amdgcn_sched_barrier(0);
;         }
; #pragma unroll
;         for (int g = 14; g < 16; ++g) { f32x2 v; v[0] = __builtin_amdgcn_exp2f(s1[2 * (g - 8)]); v[1] = __builtin_amdgcn_exp2f(s1[2 * (g - 8) + 1]); ps2 += v; w_[g] = cvtpk(v[0], v[1]); }
;     ...
;         if (j + 1 == NT - 1) {
;           ps2 = f32x2{0.f, 0.f};
; #pragma unroll
;           for (int g = 0; g < 4; ++g) { ps2[0] += __builtin_amdgcn_exp2f(s0[2 * g]); ps2[1] += __builtin_amdgcn_exp2f(s0[2 * g + 1]); }
; #pragma unroll
;           for (int g = 4; g < 16; ++g) w_[g] = 0u;
;         }
;         if (j + 1 < NT) {
;           l += ps2[0] + ps2[1];
; #pragma unroll
.Lmy_a1_skipk:
	v_mfma_f32_32x32x16_bf16 v[64:79], v[214:217], v[104:107], v[64:79]
	v_lshl_add_u64 v[240:241], s[6:7], 0, v[174:175]
	v_add_co_u32_e32 v244, vcc, 0x29900000, v240
	s_nop 1
	v_addc_co_u32_e32 v245, vcc, 0, v241, vcc
	v_add_co_u32_e32 v240, vcc, 0x29982000, v240
	s_nop 1
	v_addc_co_u32_e32 v241, vcc, 0, v241, vcc
	global_load_dwordx4 v[136:139], v[244:245], off offset:256
	global_load_dwordx4 v[140:143], v[240:241], off offset:256
	s_waitcnt lgkmcnt(11)
	v_mfma_f32_32x32x16_bf16 v[80:95], v[220:223], v[116:119], v[80:95]
	ds_read_b128 v[214:217], v177 offset:34816
	ds_read_b128 v[220:223], v177 offset:39424
	s_waitcnt lgkmcnt(11)
	v_mfma_f32_32x32x16_bf16 v[64:79], v[224:227], v[116:119], v[64:79]
	v_mfma_f32_32x32x16_bf16 v[80:95], v[228:231], v[120:123], v[80:95]
	ds_read_b128 v[224:227], v177 offset:44032
	ds_read_b128 v[228:231], v177 offset:48640
	s_waitcnt lgkmcnt(9)
	v_mfma_f32_32x32x16_bf16 v[64:79], v[178:181], v[120:123], v[64:79]
	v_mfma_f32_32x32x16_bf16 v[80:95], v[182:185], v[112:115], v[80:95]
	ds_read_b128 v[178:181], v177 offset:34848
	ds_read_b128 v[182:185], v177 offset:39456
	s_waitcnt lgkmcnt(7)
	v_mfma_f32_32x32x16_bf16 v[64:79], v[190:193], v[112:115], v[64:79]
	v_mfma_f32_32x32x16_bf16 v[80:95], v[186:189], v[124:127], v[80:95]
	ds_read_b128 v[190:193], v177 offset:44064
	ds_read_b128 v[186:189], v177 offset:48672
	s_waitcnt lgkmcnt(7)
	v_mfma_f32_32x32x16_bf16 v[64:79], v[194:197], v[124:127], v[64:79]
	v_mfma_f32_32x32x16_bf16 v[48:63], v[214:217], v[144:147], v[48:63]
	ds_read_b128 v[194:197], v177 offset:34880
	s_waitcnt lgkmcnt(7)
	v_mfma_f32_32x32x16_bf16 v[32:47], v[220:223], v[144:147], v[32:47]
	ds_read_b128 v[214:217], v177 offset:39488
	s_waitcnt lgkmcnt(7)
	v_mfma_f32_32x32x16_bf16 v[16:31], v[224:227], v[144:147], v[16:31]
	s_nop 0
	v_exp_f32_e32 v80, v80
	v_exp_f32_e32 v81, v81
	ds_read_b128 v[220:223], v177 offset:44096
	v_mov_b32_e32 v198, v80
	v_mov_b32_e32 v199, v81
	v_cvt_pk_bf16_f32 v80, v80, v81
	s_waitcnt lgkmcnt(7)
	v_mfma_f32_32x32x16_bf16 v[0:15], v[228:231], v[144:147], v[0:15]
	v_exp_f32_e32 v82, v82
	v_exp_f32_e32 v83, v83
	ds_read_b128 v[224:227], v177 offset:48704
	v_cvt_pk_bf16_f32 v145, v82, v83
	v_add_f32_e32 v198, v82, v198
	v_add_f32_e32 v199, v83, v199
	s_waitcnt lgkmcnt(7)
	v_mfma_f32_32x32x16_bf16 v[48:63], v[178:181], v[148:151], v[48:63]
	v_exp_f32_e32 v82, v84
	v_exp_f32_e32 v83, v85
	ds_read_b128 v[228:231], v177 offset:34912
	v_add_f32_e32 v84, v82, v198
	v_add_f32_e32 v85, v83, v199
	v_cvt_pk_bf16_f32 v146, v82, v83
	s_waitcnt lgkmcnt(7)
	v_mfma_f32_32x32x16_bf16 v[32:47], v[182:185], v[148:151], v[32:47]
	v_exp_f32_e32 v82, v86
	v_exp_f32_e32 v83, v87
	ds_read_b128 v[178:181], v177 offset:39520
	v_add_f32_e32 v84, v82, v84
	v_add_f32_e32 v85, v83, v85
	v_cvt_pk_bf16_f32 v147, v82, v83
	s_waitcnt lgkmcnt(7)
	v_mfma_f32_32x32x16_bf16 v[16:31], v[190:193], v[148:151], v[16:31]
	v_exp_f32_e32 v82, v88
	v_exp_f32_e32 v83, v89
	ds_read_b128 v[182:185], v177 offset:44128
	v_add_f32_e32 v86, v82, v84
	v_add_f32_e32 v87, v83, v85
	v_cvt_pk_bf16_f32 v84, v82, v83
	s_waitcnt lgkmcnt(7)
	v_mfma_f32_32x32x16_bf16 v[0:15], v[186:189], v[148:151], v[0:15]
	v_exp_f32_e32 v82, v90
	v_exp_f32_e32 v83, v91
	ds_read_b128 v[190:193], v177 offset:48736
	v_cvt_pk_bf16_f32 v149, v82, v83
	v_add_f32_e32 v86, v82, v86
	v_add_f32_e32 v87, v83, v87
	s_waitcnt lgkmcnt(7)
	v_mfma_f32_32x32x16_bf16 v[48:63], v[194:197], v[152:155], v[48:63]
	v_exp_f32_e32 v82, v92
	v_exp_f32_e32 v83, v93
	s_nop 0
	v_cvt_pk_bf16_f32 v150, v82, v83
	v_add_f32_e32 v86, v82, v86
	v_add_f32_e32 v87, v83, v87
	s_waitcnt lgkmcnt(6)
	v_mfma_f32_32x32x16_bf16 v[32:47], v[214:217], v[152:155], v[32:47]
	v_exp_f32_e32 v82, v94
	v_exp_f32_e32 v83, v95
	s_nop 0
	v_cvt_pk_bf16_f32 v151, v82, v83
	v_add_f32_e32 v86, v82, v86
	v_add_f32_e32 v87, v83, v87
	s_waitcnt lgkmcnt(5)
	v_mfma_f32_32x32x16_bf16 v[16:31], v[220:223], v[152:155], v[16:31]
	v_exp_f32_e32 v64, v64
	v_exp_f32_e32 v65, v65
	s_nop 0
	v_cvt_pk_bf16_f32 v88, v64, v65
	v_add_f32_e32 v82, v64, v86
	v_add_f32_e32 v83, v65, v87
	s_waitcnt lgkmcnt(4)
	v_mfma_f32_32x32x16_bf16 v[0:15], v[224:227], v[152:155], v[0:15]
	v_exp_f32_e32 v64, v66
	v_exp_f32_e32 v65, v67
	s_nop 0
	v_cvt_pk_bf16_f32 v153, v64, v65
	v_add_f32_e32 v66, v64, v82
	v_add_f32_e32 v67, v65, v83
	s_waitcnt lgkmcnt(3)
	v_mfma_f32_32x32x16_bf16 v[48:63], v[228:231], v[156:159], v[48:63]
	v_exp_f32_e32 v64, v68
	v_exp_f32_e32 v65, v69
	s_nop 0
	v_cvt_pk_bf16_f32 v154, v64, v65
	v_add_f32_e32 v66, v64, v66
	v_add_f32_e32 v67, v65, v67
	s_waitcnt lgkmcnt(2)
	v_mfma_f32_32x32x16_bf16 v[32:47], v[178:181], v[156:159], v[32:47]
	v_exp_f32_e32 v64, v70
	v_exp_f32_e32 v65, v71
	s_nop 0
	v_cvt_pk_bf16_f32 v155, v64, v65
	v_add_f32_e32 v66, v64, v66
	v_add_f32_e32 v67, v65, v67
	s_waitcnt lgkmcnt(1)
	v_mfma_f32_32x32x16_bf16 v[16:31], v[182:185], v[156:159], v[16:31]
	v_exp_f32_e32 v64, v72
	v_exp_f32_e32 v65, v73
	s_nop 0
	v_cvt_pk_bf16_f32 v92, v64, v65
	v_add_f32_e32 v66, v64, v66
	v_add_f32_e32 v67, v65, v67
	s_waitcnt lgkmcnt(0)
	v_mfma_f32_32x32x16_bf16 v[0:15], v[190:193], v[156:159], v[0:15]
	v_exp_f32_e32 v64, v74
	v_exp_f32_e32 v65, v75
	s_nop 0
	v_cvt_pk_bf16_f32 v157, v64, v65
	v_add_f32_e32 v64, v64, v66
	v_add_f32_e32 v65, v65, v67
	v_exp_f32_e32 v66, v76
	v_exp_f32_e32 v67, v77
	v_exp_f32_e32 v68, v78
	v_exp_f32_e32 v69, v79
	s_waitcnt lgkmcnt(0)
	v_add_f32_e32 v64, v66, v64
	v_add_f32_e32 v65, v67, v65
	s_barrier
	v_add_f32_e32 v64, v68, v64
	v_add_f32_e32 v65, v69, v65
	s_add_u32 s24, s24, 0x8000
	v_add_f32_e32 v64, v64, v65
	s_addc_u32 s25, s25, 0
	v_cvt_pk_bf16_f32 v158, v66, v67
	v_cvt_pk_bf16_f32 v159, v68, v69
	v_add_f32_e32 v176, v176, v64
	s_cmp_eq_u32 s27, 62
	v_lshl_add_u64 v[174:175], v[174:175], 0, s[16:17]
	s_cbranch_scc1 .LBB0_1215
	s_mov_b32 s42, s27
	s_branch .LBB0_1217
